# lever 8: attention K- and V-fragment ds_read_b128 hoisted ahead of their MFMAs into registers unused by the attention block (counted lgkmcnt 3/2/1/0), MFMAs issue back to back
# speedup vs baseline: 1.0028x; 1.0028x over previous
; #define LAS __attribute__((address_space(3)))
; __device__ __forceinline__ void sb_attn_wave(const bf16_t* __restrict__ P, const bf16_t* __restrict__ KHp, const bf16_t* __restrict__ Vt, bf16_t* __restrict__ mixed, int gw, int NGW, int lane, LAS unsigned char* wl) {
;     ...
; #pragma unroll
;             for (int d0 = 0; d0 < 4; ++d0) { const bf16x8 kf0 = *(const LAS bf16x8*)(kl + kro + d0 * 32); p0 = __builtin_amdgcn_mfma_f32_32x32x16_bf16(kf0, qf[d0], p0, 0, 0, 0); }
;             if (!p1_dead) {
; #pragma unroll
;                 for (int d0 = 0; d0 < 4; ++d0) { const bf16x8 kf1 = *(const LAS bf16x8*)(kl + kro + 32 * SB_PITCH + d0 * 32); p1 = __builtin_amdgcn_mfma_f32_32x32x16_bf16(kf1, qf[d0], p1, 0, 0, 0); }
;             }
.LBB0_412:
	ds_read_b128 v[32:35], v158
	ds_read_b128 v[48:51], v158 offset:32
	ds_read_b128 v[214:217], v158 offset:64
	ds_read_b128 v[218:221], v158 offset:96
	s_lshl_b32 s12, s38, 6
	s_or_b32 s4, s12, 63
	s_cmp_ge_u32 s4, s48
	s_cselect_b64 s[4:5], -1, 0
	s_and_b64 s[8:9], s[22:23], s[4:5]
	s_and_b64 vcc, exec, s[8:9]
	v_or_b32_e32 v162, s12, v146
	s_waitcnt lgkmcnt(3)
	v_mfma_f32_32x32x16_bf16 v[32:47], v[32:35], v[64:67], 0
	s_waitcnt lgkmcnt(2)
	v_mfma_f32_32x32x16_bf16 v[32:47], v[48:51], v[68:71], v[32:47]
	s_waitcnt lgkmcnt(1)
	v_mfma_f32_32x32x16_bf16 v[32:47], v[214:217], v[72:75], v[32:47]
	s_waitcnt lgkmcnt(0)
	v_mfma_f32_32x32x16_bf16 v[32:47], v[218:221], v[76:79], v[32:47]
	s_cbranch_vccnz .LBB0_414
	ds_read_b128 v[48:51], v158 offset:4608
	ds_read_b128 v[164:167], v158 offset:4640
	ds_read_b128 v[230:233], v158 offset:4672
	ds_read_b128 v[234:237], v158 offset:4704
	v_or_b32_e32 v163, 48, v162
	v_cmp_lt_u32_e32 vcc, v163, v160
	s_waitcnt lgkmcnt(3)
	v_mfma_f32_32x32x16_bf16 v[48:63], v[48:51], v[64:67], 0
	s_waitcnt lgkmcnt(2)
	v_mfma_f32_32x32x16_bf16 v[48:63], v[164:167], v[68:71], v[48:63]
	s_waitcnt lgkmcnt(1)
	v_mfma_f32_32x32x16_bf16 v[48:63], v[230:233], v[72:75], v[48:63]
	s_waitcnt lgkmcnt(0)
	v_mfma_f32_32x32x16_bf16 v[48:63], v[234:237], v[76:79], v[48:63]
	s_cmp_eq_u64 s[4:5], 0
	s_cbranch_scc1 .Lsb_p1_nomask
	ds_read_b128 v[198:201], v159 offset:9280
	ds_read_b128 v[202:205], v159 offset:9312
	ds_read_b128 v[206:209], v159 offset:13920
	ds_read_b128 v[210:213], v159 offset:13888
	s_nop 11
	v_exp_f32_e32 v56, v56
	v_exp_f32_e32 v57, v57
	v_exp_f32_e32 v58, v58
	v_exp_f32_e32 v59, v59
	v_add_f32_e32 v56, 1.0, v56
	v_rcp_f32_e32 v56, v56
	v_add_f32_e32 v57, 1.0, v57
	v_rcp_f32_e32 v57, v57
	v_add_f32_e32 v58, 1.0, v58
	v_sub_f32_e32 v164, 1.0, v56
	v_cndmask_b32_e32 v163, 1.0, v56, vcc
	v_cndmask_b32_e32 v165, 0, v164, vcc
	v_cndmask_b32_e64 v166, v56, v163, s[4:5]
	v_cndmask_b32_e64 v56, v164, v165, s[4:5]
	v_or_b32_e32 v164, 49, v162
	v_cmp_lt_u32_e32 vcc, v164, v160
	v_rcp_f32_e32 v58, v58
	v_sub_f32_e32 v163, 1.0, v57
	v_cndmask_b32_e32 v164, 1.0, v57, vcc
	v_exp_f32_e32 v60, v60
	v_cndmask_b32_e32 v165, 0, v163, vcc
	v_cndmask_b32_e64 v57, v57, v164, s[4:5]
	v_add_f32_e32 v59, 1.0, v59
	v_cndmask_b32_e64 v163, v163, v165, s[4:5]
	v_mul_f32_e32 v165, v166, v57
	v_or_b32_e32 v166, 50, v162
	v_rcp_f32_e32 v59, v59
	v_sub_f32_e32 v164, 1.0, v58
	v_cmp_lt_u32_e32 vcc, v166, v160
	v_exp_f32_e32 v61, v61
	v_add_f32_e32 v60, 1.0, v60
	v_cndmask_b32_e32 v166, 1.0, v58, vcc
	v_cndmask_b32_e32 v167, 0, v164, vcc
	v_cndmask_b32_e64 v58, v58, v166, s[4:5]
	v_cndmask_b32_e64 v164, v164, v167, s[4:5]
	v_or_b32_e32 v167, 51, v162
	v_rcp_f32_e32 v60, v60
	v_mul_f32_e32 v166, v58, v165
	v_sub_f32_e32 v165, 1.0, v59
	v_cmp_lt_u32_e32 vcc, v167, v160
	v_exp_f32_e32 v62, v62
	v_add_f32_e32 v61, 1.0, v61
	v_cndmask_b32_e32 v167, 1.0, v59, vcc
	v_cndmask_b32_e32 v168, 0, v165, vcc
	v_cndmask_b32_e64 v59, v59, v167, s[4:5]
	v_cndmask_b32_e64 v165, v165, v168, s[4:5]
	v_or_b32_e32 v168, 52, v162
	v_rcp_f32_e32 v61, v61
	v_mul_f32_e32 v167, v59, v166
	v_sub_f32_e32 v166, 1.0, v60
	v_cmp_lt_u32_e32 vcc, v168, v160
	v_add_f32_e32 v62, 1.0, v62
	v_exp_f32_e32 v63, v63
	v_cndmask_b32_e32 v168, 1.0, v60, vcc
	v_cndmask_b32_e32 v169, 0, v166, vcc
	v_cndmask_b32_e64 v60, v60, v168, s[4:5]
	v_cndmask_b32_e64 v166, v166, v169, s[4:5]
	v_or_b32_e32 v169, 53, v162
	v_rcp_f32_e32 v62, v62
	v_mul_f32_e32 v168, v60, v167
	v_sub_f32_e32 v167, 1.0, v61
	v_cmp_lt_u32_e32 vcc, v169, v160
	v_exp_f32_e32 v48, v48
	v_add_f32_e32 v63, 1.0, v63
	v_cndmask_b32_e32 v169, 1.0, v61, vcc
	v_cndmask_b32_e32 v170, 0, v167, vcc
	v_cndmask_b32_e64 v61, v61, v169, s[4:5]
	v_cndmask_b32_e64 v167, v167, v170, s[4:5]
	v_or_b32_e32 v170, 54, v162
	v_mul_f32_e32 v169, v61, v168
	v_sub_f32_e32 v168, 1.0, v62
	v_cmp_lt_u32_e32 vcc, v170, v160
	v_rcp_f32_e32 v63, v63
	v_add_f32_e32 v48, 1.0, v48
	v_cndmask_b32_e32 v171, 0, v168, vcc
	v_cndmask_b32_e64 v168, v168, v171, s[4:5]
	v_or_b32_e32 v171, 55, v162
	v_exp_f32_e32 v49, v49
	v_cndmask_b32_e32 v170, 1.0, v62, vcc
	v_cmp_lt_u32_e32 vcc, v171, v160
	v_rcp_f32_e32 v48, v48
	v_cndmask_b32_e64 v62, v62, v170, s[4:5]
	v_cndmask_b32_e32 v171, 1.0, v63, vcc
	v_mul_f32_e32 v170, v62, v169
	v_sub_f32_e32 v169, 1.0, v63
	v_cndmask_b32_e64 v63, v63, v171, s[4:5]
	v_exp_f32_e32 v50, v50
	v_cndmask_b32_e32 v172, 0, v169, vcc
	v_mul_f32_e32 v171, v63, v170
	v_or_b32_e32 v170, 32, v162
	v_add_f32_e32 v49, 1.0, v49
	v_cndmask_b32_e64 v169, v169, v172, s[4:5]
	v_sub_f32_e32 v172, 1.0, v48
	v_cmp_lt_u32_e32 vcc, v170, v160
	v_rcp_f32_e32 v49, v49
	v_add_f32_e32 v50, 1.0, v50
	v_cndmask_b32_e32 v170, 1.0, v48, vcc
	v_cndmask_b32_e32 v173, 0, v172, vcc
	v_cndmask_b32_e64 v174, v48, v170, s[4:5]
	v_cndmask_b32_e64 v48, v172, v173, s[4:5]
	v_or_b32_e32 v172, 33, v162
	v_exp_f32_e32 v51, v51
	v_cmp_lt_u32_e32 vcc, v172, v160
	v_rcp_f32_e32 v50, v50
	v_sub_f32_e32 v170, 1.0, v49
	v_cndmask_b32_e32 v172, 1.0, v49, vcc
	v_cndmask_b32_e64 v49, v49, v172, s[4:5]
	v_cndmask_b32_e32 v173, 0, v170, vcc
	v_mul_f32_e32 v172, v174, v49
	v_or_b32_e32 v174, 34, v162
	v_add_f32_e32 v51, 1.0, v51
	v_cndmask_b32_e64 v170, v170, v173, s[4:5]
	v_sub_f32_e32 v173, 1.0, v50
	v_cmp_lt_u32_e32 vcc, v174, v160
	v_rcp_f32_e32 v51, v51
	s_nop 0
	v_cndmask_b32_e32 v175, 0, v173, vcc
	v_cndmask_b32_e64 v173, v173, v175, s[4:5]
	v_or_b32_e32 v175, 35, v162
	v_cndmask_b32_e32 v174, 1.0, v50, vcc
	v_cmp_lt_u32_e32 vcc, v175, v160
	v_cndmask_b32_e64 v174, v50, v174, s[4:5]
	v_mul_f32_e32 v50, v174, v172
	v_cndmask_b32_e32 v175, 1.0, v51, vcc
	v_sub_f32_e32 v172, 1.0, v51
; __device__ __forceinline__ void sb_attn_wave(const bf16_t* __restrict__ P, const bf16_t* __restrict__ KHp, const bf16_t* __restrict__ Vt, bf16_t* __restrict__ mixed, int gw, int NGW, int lane, LAS unsigned char* wl) {
;     ...
;             float cmid = carry;
;             if (!p1_dead) SB_HALF(p1, 3, 2, carry, cmid);
;             const bool done_mid = __all(cmid < 5.421010862427522e-20f);
;             if (!done_mid) SB_HALF(p0, 1, 0, cmid, carry); else carry = cmid;
	v_cndmask_b32_e64 v175, v51, v175, s[4:5]
	v_exp_f32_e32 v51, v52
	v_cndmask_b32_e32 v176, 0, v172, vcc
	v_cndmask_b32_e64 v172, v172, v176, s[4:5]
	v_or_b32_e32 v176, 36, v162
	v_add_f32_e32 v51, 1.0, v51
	v_rcp_f32_e32 v51, v51
	v_cmp_lt_u32_e32 vcc, v176, v160
	v_mul_f32_e32 v50, v175, v50
	v_sub_f32_e32 v52, 1.0, v51
	v_cndmask_b32_e32 v176, 1.0, v51, vcc
	v_cndmask_b32_e64 v176, v51, v176, s[4:5]
	v_exp_f32_e32 v51, v53
	v_or_b32_e32 v53, 37, v162
	v_cndmask_b32_e32 v177, 0, v52, vcc
	v_cmp_lt_u32_e32 vcc, v53, v160
	v_add_f32_e32 v51, 1.0, v51
	v_rcp_f32_e32 v51, v51
	v_cndmask_b32_e64 v177, v52, v177, s[4:5]
	v_mul_f32_e32 v50, v176, v50
	v_cndmask_b32_e32 v53, 1.0, v51, vcc
	v_sub_f32_e32 v52, 1.0, v51
	v_cndmask_b32_e64 v179, v51, v53, s[4:5]
	v_exp_f32_e32 v51, v54
	v_or_b32_e32 v53, 38, v162
	v_cndmask_b32_e32 v178, 0, v52, vcc
	v_cmp_lt_u32_e32 vcc, v53, v160
	v_add_f32_e32 v51, 1.0, v51
	v_rcp_f32_e32 v51, v51
	v_cndmask_b32_e64 v178, v52, v178, s[4:5]
	v_mul_f32_e32 v50, v179, v50
	v_cndmask_b32_e32 v53, 1.0, v51, vcc
	v_sub_f32_e32 v52, 1.0, v51
	v_cndmask_b32_e64 v180, v51, v53, s[4:5]
	v_exp_f32_e32 v51, v55
	v_or_b32_e32 v53, 39, v162
	v_cndmask_b32_e32 v54, 0, v52, vcc
	v_cmp_lt_u32_e32 vcc, v53, v160
	v_add_f32_e32 v51, 1.0, v51
	v_rcp_f32_e32 v51, v51
	v_mul_f32_e32 v50, v180, v50
	v_cndmask_b32_e64 v181, v52, v54, s[4:5]
	v_cndmask_b32_e32 v53, 1.0, v51, vcc
	v_cndmask_b32_e64 v182, v51, v53, s[4:5]
	v_mul_f32_e32 v50, v182, v50
	v_sub_f32_e32 v52, 1.0, v51
	ds_bpermute_b32 v51, v156, v171
	ds_bpermute_b32 v184, v156, v50
	v_cndmask_b32_e32 v54, 0, v52, vcc
	v_cndmask_b32_e64 v183, v52, v54, s[4:5]
	s_waitcnt lgkmcnt(1)
	v_mul_f32_e32 v52, v171, v51
	s_waitcnt lgkmcnt(0)
	v_mul_f32_e32 v185, v50, v184
	v_cndmask_b32_e64 v50, 1.0, v51, s[6:7]
	v_mul_f32_e32 v50, v161, v50
	v_mul_f32_e32 v53, v50, v169
	v_mul_f32_e32 v50, v50, v63
	v_mul_f32_e32 v54, v50, v168
	v_mul_f32_e32 v50, v62, v50
	v_mul_f32_e32 v171, v161, v52
	v_mul_f32_e32 v52, v167, v50
	v_mul_f32_e32 v50, v61, v50
	v_mul_f32_e32 v55, v166, v50
	v_mul_f32_e32 v50, v60, v50
	v_mul_f32_e32 v51, v165, v50
	v_mul_f32_e32 v50, v59, v50
	v_mul_f32_e32 v59, v164, v50
	v_mul_f32_e32 v50, v58, v50
	v_mul_f32_e32 v58, v163, v50
	v_mul_f32_e32 v50, v57, v50
	v_mul_f32_e32 v50, v56, v50
	v_cvt_pk_bf16_f32 v50, v50, v58
	v_cvt_pk_bf16_f32 v51, v59, v51
	v_cvt_pk_bf16_f32 v52, v55, v52
	v_cvt_pk_bf16_f32 v53, v54, v53
	s_waitcnt lgkmcnt(1)
	v_mfma_f32_32x32x16_bf16 v[16:31], v[202:205], v[50:53], v[16:31]
	v_mul_f32_e32 v161, v185, v171
	s_waitcnt lgkmcnt(0)
	v_mfma_f32_32x32x16_bf16 v[0:15], v[206:209], v[50:53], v[0:15]
	v_cndmask_b32_e64 v50, 1.0, v184, s[6:7]
	v_mul_f32_e32 v50, v50, v171
	v_mul_f32_e32 v51, v183, v50
	v_mul_f32_e32 v50, v182, v50
	v_mul_f32_e32 v52, v181, v50
	v_mul_f32_e32 v50, v180, v50
	v_mul_f32_e32 v53, v178, v50
	v_mul_f32_e32 v50, v179, v50
	v_mul_f32_e32 v58, v177, v50
	v_mul_f32_e32 v50, v176, v50
	v_mul_f32_e32 v59, v172, v50
	v_mul_f32_e32 v50, v175, v50
	v_mul_f32_e32 v60, v173, v50
	v_mul_f32_e32 v50, v174, v50
	v_mul_f32_e32 v49, v49, v50
	v_mul_f32_e32 v61, v170, v50
	v_mul_f32_e32 v48, v48, v49
	v_cvt_pk_bf16_f32 v48, v48, v61
	v_cvt_pk_bf16_f32 v49, v60, v59
	v_cvt_pk_bf16_f32 v50, v58, v53
	v_cvt_pk_bf16_f32 v51, v52, v51
	s_nop 1
	v_mfma_f32_32x32x16_bf16 v[16:31], v[198:201], v[48:51], v[16:31]
	s_waitcnt lgkmcnt(0)
	v_mfma_f32_32x32x16_bf16 v[0:15], v[210:213], v[48:51], v[0:15]
.LBB0_414:
	v_cmp_gt_f32_e32 vcc, s34, v161
	s_cmp_eq_u64 vcc, exec
	s_cselect_b64 vcc, -1, 0
	s_cbranch_vccnz .LBB0_416
	ds_read_b128 v[198:201], v159 offset:9216
	ds_read_b128 v[202:205], v159 offset:9248
	ds_read_b128 v[206:209], v159 offset:13856
	ds_read_b128 v[210:213], v159 offset:13824
	s_cmp_eq_u64 s[4:5], 0
	s_cbranch_scc1 .Lsb_p0_nomask
	s_nop 6
	v_exp_f32_e32 v40, v40
	v_exp_f32_e32 v41, v41
	v_exp_f32_e32 v42, v42
	v_or_b32_e32 v48, 16, v162
	v_add_f32_e32 v40, 1.0, v40
	v_rcp_f32_e32 v40, v40
	v_add_f32_e32 v41, 1.0, v41
	v_cmp_lt_u32_e64 s[8:9], v48, v160
	v_rcp_f32_e32 v41, v41
	v_sub_f32_e32 v49, 1.0, v40
	v_cndmask_b32_e64 v48, 1.0, v40, s[8:9]
	v_cndmask_b32_e64 v50, 0, v49, s[8:9]
	v_exp_f32_e32 v43, v43
	v_cndmask_b32_e64 v51, v40, v48, s[4:5]
	v_cndmask_b32_e64 v40, v49, v50, s[4:5]
	v_or_b32_e32 v49, 17, v162
	v_add_f32_e32 v42, 1.0, v42
	v_cmp_lt_u32_e64 s[8:9], v49, v160
	v_rcp_f32_e32 v42, v42
	v_sub_f32_e32 v48, 1.0, v41
	v_cndmask_b32_e64 v49, 1.0, v41, s[8:9]
	v_exp_f32_e32 v44, v44
	v_cndmask_b32_e64 v50, 0, v48, s[8:9]
	v_cndmask_b32_e64 v41, v41, v49, s[4:5]
	v_add_f32_e32 v43, 1.0, v43
	v_cndmask_b32_e64 v48, v48, v50, s[4:5]
	v_mul_f32_e32 v50, v51, v41
	v_or_b32_e32 v51, 18, v162
	v_rcp_f32_e32 v43, v43
	v_sub_f32_e32 v49, 1.0, v42
	v_cmp_lt_u32_e64 s[8:9], v51, v160
	v_exp_f32_e32 v45, v45
	v_add_f32_e32 v44, 1.0, v44
	v_cndmask_b32_e64 v51, 1.0, v42, s[8:9]
	v_cndmask_b32_e64 v52, 0, v49, s[8:9]
	v_cndmask_b32_e64 v42, v42, v51, s[4:5]
	v_cndmask_b32_e64 v49, v49, v52, s[4:5]
	v_or_b32_e32 v52, 19, v162
	v_rcp_f32_e32 v44, v44
	v_mul_f32_e32 v51, v42, v50
	v_sub_f32_e32 v50, 1.0, v43
	v_cmp_lt_u32_e64 s[8:9], v52, v160
	v_exp_f32_e32 v46, v46
	v_add_f32_e32 v45, 1.0, v45
	v_cndmask_b32_e64 v52, 1.0, v43, s[8:9]
	v_cndmask_b32_e64 v53, 0, v50, s[8:9]
	v_cndmask_b32_e64 v43, v43, v52, s[4:5]
	v_cndmask_b32_e64 v50, v50, v53, s[4:5]
	v_or_b32_e32 v53, 20, v162
	v_rcp_f32_e32 v45, v45
	v_mul_f32_e32 v52, v43, v51
	v_sub_f32_e32 v51, 1.0, v44
	v_cmp_lt_u32_e64 s[8:9], v53, v160
	v_add_f32_e32 v46, 1.0, v46
	v_exp_f32_e32 v47, v47
	v_cndmask_b32_e64 v53, 1.0, v44, s[8:9]
	v_cndmask_b32_e64 v54, 0, v51, s[8:9]
	v_cndmask_b32_e64 v44, v44, v53, s[4:5]
	v_cndmask_b32_e64 v51, v51, v54, s[4:5]
	v_or_b32_e32 v54, 21, v162
	v_rcp_f32_e32 v46, v46
	v_mul_f32_e32 v53, v44, v52
	v_sub_f32_e32 v52, 1.0, v45
	v_cmp_lt_u32_e64 s[8:9], v54, v160
	v_exp_f32_e32 v32, v32
	v_add_f32_e32 v47, 1.0, v47
	v_cndmask_b32_e64 v54, 1.0, v45, s[8:9]
	v_cndmask_b32_e64 v55, 0, v52, s[8:9]
	v_cndmask_b32_e64 v45, v45, v54, s[4:5]
	v_cndmask_b32_e64 v52, v52, v55, s[4:5]
	v_or_b32_e32 v55, 22, v162
	v_mul_f32_e32 v54, v45, v53
	v_sub_f32_e32 v53, 1.0, v46
	v_cmp_lt_u32_e64 s[8:9], v55, v160
	v_rcp_f32_e32 v47, v47
	v_exp_f32_e32 v33, v33
	v_cndmask_b32_e64 v56, 0, v53, s[8:9]
	v_add_f32_e32 v32, 1.0, v32
	v_cndmask_b32_e64 v53, v53, v56, s[4:5]
	v_or_b32_e32 v56, 23, v162
	v_rcp_f32_e32 v32, v32
	v_cndmask_b32_e64 v55, 1.0, v46, s[8:9]
	v_cmp_lt_u32_e64 s[8:9], v56, v160
	v_exp_f32_e32 v34, v34
	v_cndmask_b32_e64 v46, v46, v55, s[4:5]
	v_cndmask_b32_e64 v56, 1.0, v47, s[8:9]
	v_add_f32_e32 v33, 1.0, v33
	v_mul_f32_e32 v55, v46, v54
	v_sub_f32_e32 v54, 1.0, v47
	v_cndmask_b32_e64 v47, v47, v56, s[4:5]
	v_rcp_f32_e32 v33, v33
	v_cndmask_b32_e64 v57, 0, v54, s[8:9]
	v_mul_f32_e32 v56, v47, v55
	v_sub_f32_e32 v55, 1.0, v32
	v_cmp_lt_u32_e64 s[8:9], v162, v160
	v_cndmask_b32_e64 v54, v54, v57, s[4:5]
	v_add_f32_e32 v34, 1.0, v34
	v_cndmask_b32_e64 v57, 1.0, v32, s[8:9]
	v_cndmask_b32_e64 v58, 0, v55, s[8:9]
	v_exp_f32_e32 v35, v35
	v_cndmask_b32_e64 v57, v32, v57, s[4:5]
	v_cndmask_b32_e64 v32, v55, v58, s[4:5]
	v_or_b32_e32 v58, 1, v162
	v_rcp_f32_e32 v34, v34
	v_sub_f32_e32 v55, 1.0, v33
	v_cmp_lt_u32_e64 s[8:9], v58, v160
	v_add_f32_e32 v35, 1.0, v35
	v_rcp_f32_e32 v35, v35
	v_cndmask_b32_e64 v59, 0, v55, s[8:9]
	v_cndmask_b32_e64 v58, 1.0, v33, s[8:9]
	v_cndmask_b32_e64 v55, v55, v59, s[4:5]
	v_or_b32_e32 v59, 2, v162
	v_cndmask_b32_e64 v33, v33, v58, s[4:5]
	v_sub_f32_e32 v58, 1.0, v34
	v_cmp_lt_u32_e64 s[8:9], v59, v160
	v_mul_f32_e32 v57, v57, v33
	s_nop 0
	v_cndmask_b32_e64 v60, 0, v58, s[8:9]
	v_cndmask_b32_e64 v58, v58, v60, s[4:5]
	v_or_b32_e32 v60, 3, v162
	v_cndmask_b32_e64 v59, 1.0, v34, s[8:9]
	v_cmp_lt_u32_e64 s[8:9], v60, v160
	v_cndmask_b32_e64 v59, v34, v59, s[4:5]
	v_mul_f32_e32 v34, v59, v57
	v_cndmask_b32_e64 v60, 1.0, v35, s[8:9]
	v_sub_f32_e32 v57, 1.0, v35
	v_cndmask_b32_e64 v60, v35, v60, s[4:5]
	v_exp_f32_e32 v35, v36
	v_cndmask_b32_e64 v61, 0, v57, s[8:9]
	v_cndmask_b32_e64 v57, v57, v61, s[4:5]
	v_or_b32_e32 v61, 4, v162
	v_add_f32_e32 v35, 1.0, v35
	v_rcp_f32_e32 v35, v35
	v_cmp_lt_u32_e64 s[8:9], v61, v160
	v_mul_f32_e32 v34, v60, v34
	v_sub_f32_e32 v36, 1.0, v35
	v_cndmask_b32_e64 v61, 1.0, v35, s[8:9]
	v_cndmask_b32_e64 v61, v35, v61, s[4:5]
	v_exp_f32_e32 v35, v37
	v_or_b32_e32 v37, 5, v162
	v_cndmask_b32_e64 v62, 0, v36, s[8:9]
	v_cmp_lt_u32_e64 s[8:9], v37, v160
	v_add_f32_e32 v35, 1.0, v35
	v_rcp_f32_e32 v35, v35
	v_cndmask_b32_e64 v62, v36, v62, s[4:5]
	v_mul_f32_e32 v34, v61, v34
	v_cndmask_b32_e64 v37, 1.0, v35, s[8:9]
	v_sub_f32_e32 v36, 1.0, v35
	v_cndmask_b32_e64 v163, v35, v37, s[4:5]
	v_exp_f32_e32 v35, v38
	v_or_b32_e32 v37, 6, v162
	v_cndmask_b32_e64 v63, 0, v36, s[8:9]
	v_cmp_lt_u32_e64 s[8:9], v37, v160
	v_add_f32_e32 v35, 1.0, v35
	v_rcp_f32_e32 v35, v35
	v_cndmask_b32_e64 v63, v36, v63, s[4:5]
	v_mul_f32_e32 v34, v163, v34
	v_cndmask_b32_e64 v37, 1.0, v35, s[8:9]
	v_sub_f32_e32 v36, 1.0, v35
	v_cndmask_b32_e64 v164, v35, v37, s[4:5]
	v_exp_f32_e32 v35, v39
	v_or_b32_e32 v37, 7, v162
	v_cndmask_b32_e64 v38, 0, v36, s[8:9]
	v_cmp_lt_u32_e64 s[8:9], v37, v160
	v_add_f32_e32 v35, 1.0, v35
	v_rcp_f32_e32 v35, v35
	v_mul_f32_e32 v34, v164, v34
	v_cndmask_b32_e64 v165, v36, v38, s[4:5]
	v_cndmask_b32_e64 v37, 1.0, v35, s[8:9]
	v_cndmask_b32_e64 v162, v35, v37, s[4:5]
	v_mul_f32_e32 v34, v162, v34
	v_sub_f32_e32 v36, 1.0, v35
	ds_bpermute_b32 v35, v156, v56
	ds_bpermute_b32 v167, v156, v34
	v_cndmask_b32_e64 v38, 0, v36, s[8:9]
	v_cndmask_b32_e64 v166, v36, v38, s[4:5]
	s_waitcnt lgkmcnt(1)
	v_mul_f32_e32 v36, v56, v35
	s_waitcnt lgkmcnt(0)
	v_mul_f32_e32 v168, v34, v167
	v_cndmask_b32_e64 v34, 1.0, v35, s[6:7]
	v_mul_f32_e32 v34, v161, v34
	v_mul_f32_e32 v37, v54, v34
	v_mul_f32_e32 v34, v47, v34
	v_mul_f32_e32 v38, v53, v34
	v_mul_f32_e32 v34, v46, v34
	v_mul_f32_e32 v56, v161, v36
	v_mul_f32_e32 v36, v52, v34
	v_mul_f32_e32 v34, v45, v34
	v_mul_f32_e32 v39, v51, v34
	v_mul_f32_e32 v34, v44, v34
	v_mul_f32_e32 v35, v50, v34
	v_mul_f32_e32 v34, v43, v34
	v_mul_f32_e32 v43, v49, v34
	v_mul_f32_e32 v34, v42, v34
	v_mul_f32_e32 v42, v48, v34
	v_mul_f32_e32 v34, v41, v34
	v_mul_f32_e32 v34, v40, v34
	v_cvt_pk_bf16_f32 v34, v34, v42
	v_cvt_pk_bf16_f32 v35, v43, v35
	v_cvt_pk_bf16_f32 v36, v39, v36
	v_cvt_pk_bf16_f32 v37, v38, v37
	s_waitcnt lgkmcnt(1)
	v_mfma_f32_32x32x16_bf16 v[16:31], v[202:205], v[34:37], v[16:31]
	v_mul_f32_e32 v161, v56, v168
	s_waitcnt lgkmcnt(0)
	v_mfma_f32_32x32x16_bf16 v[0:15], v[206:209], v[34:37], v[0:15]
	v_cndmask_b32_e64 v34, 1.0, v167, s[6:7]
	v_mul_f32_e32 v34, v56, v34
	v_mul_f32_e32 v35, v166, v34
	v_mul_f32_e32 v34, v162, v34
	v_mul_f32_e32 v36, v165, v34
	v_mul_f32_e32 v34, v164, v34
	v_mul_f32_e32 v37, v63, v34
	v_mul_f32_e32 v34, v163, v34
	v_mul_f32_e32 v42, v62, v34
	v_mul_f32_e32 v34, v61, v34
	v_mul_f32_e32 v43, v57, v34
	v_mul_f32_e32 v34, v60, v34
	v_mul_f32_e32 v44, v58, v34
	v_mul_f32_e32 v34, v59, v34
	v_mul_f32_e32 v33, v33, v34
	v_mul_f32_e32 v45, v55, v34
	v_mul_f32_e32 v32, v32, v33
	v_cvt_pk_bf16_f32 v32, v32, v45
	v_cvt_pk_bf16_f32 v33, v44, v43
	v_cvt_pk_bf16_f32 v34, v42, v37
	v_cvt_pk_bf16_f32 v35, v36, v35
	s_nop 1
	v_mfma_f32_32x32x16_bf16 v[16:31], v[198:201], v[32:35], v[16:31]
	s_waitcnt lgkmcnt(0)
	v_mfma_f32_32x32x16_bf16 v[0:15], v[210:213], v[32:35], v[0:15]

; __device__ __forceinline__ void sb_attn_wave(const bf16_t* __restrict__ P, const bf16_t* __restrict__ KHp, const bf16_t* __restrict__ Vt, bf16_t* __restrict__ mixed, int gw, int NGW, int lane, LAS unsigned char* wl) {
;     ...
;             float cmid = carry;
;             if (!p1_dead) SB_HALF(p1, 3, 2, carry, cmid);
.Lsb_p1_nomask:
	ds_read_b128 v[198:201], v159 offset:9280
	ds_read_b128 v[202:205], v159 offset:9312
	ds_read_b128 v[206:209], v159 offset:13920
	ds_read_b128 v[210:213], v159 offset:13888
	s_nop 11
	v_exp_f32_e32 v56, v56
	v_exp_f32_e32 v57, v57
	v_exp_f32_e32 v58, v58
	v_exp_f32_e32 v59, v59
	v_add_f32_e32 v56, 1.0, v56
	v_rcp_f32_e32 v56, v56
	v_add_f32_e32 v57, 1.0, v57
	v_rcp_f32_e32 v57, v57
	v_add_f32_e32 v58, 1.0, v58
	v_sub_f32_e32 v164, 1.0, v56
	v_mov_b32_e32 v166, v56
	v_mov_b32_e32 v56, v164
	v_rcp_f32_e32 v58, v58
	v_sub_f32_e32 v163, 1.0, v57
	v_exp_f32_e32 v60, v60
	v_add_f32_e32 v59, 1.0, v59
	v_mul_f32_e32 v165, v166, v57
	v_rcp_f32_e32 v59, v59
	v_sub_f32_e32 v164, 1.0, v58
	v_exp_f32_e32 v61, v61
	v_add_f32_e32 v60, 1.0, v60
	v_rcp_f32_e32 v60, v60
	v_mul_f32_e32 v166, v58, v165
	v_sub_f32_e32 v165, 1.0, v59
	v_exp_f32_e32 v62, v62
	v_add_f32_e32 v61, 1.0, v61
	v_rcp_f32_e32 v61, v61
	v_mul_f32_e32 v167, v59, v166
	v_sub_f32_e32 v166, 1.0, v60
	v_add_f32_e32 v62, 1.0, v62
	v_exp_f32_e32 v63, v63
	v_rcp_f32_e32 v62, v62
	v_mul_f32_e32 v168, v60, v167
	v_sub_f32_e32 v167, 1.0, v61
	v_exp_f32_e32 v48, v48
	v_add_f32_e32 v63, 1.0, v63
	v_mul_f32_e32 v169, v61, v168
	v_sub_f32_e32 v168, 1.0, v62
	v_rcp_f32_e32 v63, v63
	v_add_f32_e32 v48, 1.0, v48
	v_exp_f32_e32 v49, v49
	v_rcp_f32_e32 v48, v48
	v_mul_f32_e32 v170, v62, v169
	v_sub_f32_e32 v169, 1.0, v63
	v_exp_f32_e32 v50, v50
	v_mul_f32_e32 v171, v63, v170
	v_add_f32_e32 v49, 1.0, v49
	v_sub_f32_e32 v172, 1.0, v48
	v_rcp_f32_e32 v49, v49
	v_add_f32_e32 v50, 1.0, v50
	v_mov_b32_e32 v174, v48
	v_mov_b32_e32 v48, v172
	v_exp_f32_e32 v51, v51
	v_rcp_f32_e32 v50, v50
	v_sub_f32_e32 v170, 1.0, v49
	v_mul_f32_e32 v172, v174, v49
	v_add_f32_e32 v51, 1.0, v51
	v_sub_f32_e32 v173, 1.0, v50
	v_rcp_f32_e32 v51, v51
	s_nop 0
	v_mov_b32_e32 v174, v50
	v_mul_f32_e32 v50, v174, v172
	v_sub_f32_e32 v172, 1.0, v51
	v_mov_b32_e32 v175, v51
	v_exp_f32_e32 v51, v52
	s_nop 0
	v_add_f32_e32 v51, 1.0, v51
	v_rcp_f32_e32 v51, v51
	v_mul_f32_e32 v50, v175, v50
	v_sub_f32_e32 v52, 1.0, v51
	v_mov_b32_e32 v176, v51
	v_exp_f32_e32 v51, v53
	s_nop 0
	v_add_f32_e32 v51, 1.0, v51
	v_rcp_f32_e32 v51, v51
	v_mov_b32_e32 v177, v52
	v_mul_f32_e32 v50, v176, v50
	v_sub_f32_e32 v52, 1.0, v51
	v_mov_b32_e32 v179, v51
	v_exp_f32_e32 v51, v54
	s_nop 0
	v_add_f32_e32 v51, 1.0, v51
	v_rcp_f32_e32 v51, v51
	v_mov_b32_e32 v178, v52
	v_mul_f32_e32 v50, v179, v50
	v_sub_f32_e32 v52, 1.0, v51
	v_mov_b32_e32 v180, v51
	v_exp_f32_e32 v51, v55
	s_nop 0
	v_add_f32_e32 v51, 1.0, v51
	v_rcp_f32_e32 v51, v51
	v_mul_f32_e32 v50, v180, v50
	v_mov_b32_e32 v181, v52
	v_mov_b32_e32 v182, v51
	v_mul_f32_e32 v50, v182, v50
	v_sub_f32_e32 v52, 1.0, v51
	ds_bpermute_b32 v51, v156, v171
	ds_bpermute_b32 v184, v156, v50
	v_mov_b32_e32 v183, v52
	s_waitcnt lgkmcnt(1)
	v_mul_f32_e32 v52, v171, v51
	s_waitcnt lgkmcnt(0)
	v_mul_f32_e32 v185, v50, v184
	v_cndmask_b32_e64 v50, 1.0, v51, s[6:7]
	v_mul_f32_e32 v50, v161, v50
	v_mul_f32_e32 v53, v50, v169
	v_mul_f32_e32 v50, v50, v63
	v_mul_f32_e32 v54, v50, v168
	v_mul_f32_e32 v50, v62, v50
	v_mul_f32_e32 v171, v161, v52
	v_mul_f32_e32 v52, v167, v50
	v_mul_f32_e32 v50, v61, v50
	v_mul_f32_e32 v55, v166, v50
	v_mul_f32_e32 v50, v60, v50
	v_mul_f32_e32 v51, v165, v50
	v_mul_f32_e32 v50, v59, v50
	v_mul_f32_e32 v59, v164, v50
	v_mul_f32_e32 v50, v58, v50
	v_mul_f32_e32 v58, v163, v50
	v_mul_f32_e32 v50, v57, v50
	v_mul_f32_e32 v50, v56, v50
	v_cvt_pk_bf16_f32 v50, v50, v58
	v_cvt_pk_bf16_f32 v51, v59, v51
	v_cvt_pk_bf16_f32 v52, v55, v52
	v_cvt_pk_bf16_f32 v53, v54, v53
	s_waitcnt lgkmcnt(1)
	v_mfma_f32_32x32x16_bf16 v[16:31], v[202:205], v[50:53], v[16:31]
	v_mul_f32_e32 v161, v185, v171
	s_waitcnt lgkmcnt(0)
	v_mfma_f32_32x32x16_bf16 v[0:15], v[206:209], v[50:53], v[0:15]
	v_cndmask_b32_e64 v50, 1.0, v184, s[6:7]
	v_mul_f32_e32 v50, v50, v171
	v_mul_f32_e32 v51, v183, v50
	v_mul_f32_e32 v50, v182, v50
	v_mul_f32_e32 v52, v181, v50
	v_mul_f32_e32 v50, v180, v50
	v_mul_f32_e32 v53, v178, v50
	v_mul_f32_e32 v50, v179, v50
	v_mul_f32_e32 v58, v177, v50
	v_mul_f32_e32 v50, v176, v50
	v_mul_f32_e32 v59, v172, v50
	v_mul_f32_e32 v50, v175, v50
	v_mul_f32_e32 v60, v173, v50
	v_mul_f32_e32 v50, v174, v50
	v_mul_f32_e32 v49, v49, v50
	v_mul_f32_e32 v61, v170, v50
	v_mul_f32_e32 v48, v48, v49
	v_cvt_pk_bf16_f32 v48, v48, v61
	v_cvt_pk_bf16_f32 v49, v60, v59
	v_cvt_pk_bf16_f32 v50, v58, v53
	v_cvt_pk_bf16_f32 v51, v52, v51
	s_nop 1
	v_mfma_f32_32x32x16_bf16 v[16:31], v[198:201], v[48:51], v[16:31]
	s_waitcnt lgkmcnt(0)
	v_mfma_f32_32x32x16_bf16 v[0:15], v[210:213], v[48:51], v[0:15]
	s_branch .LBB0_414
; __device__ __forceinline__ void sb_attn_wave(const bf16_t* __restrict__ P, const bf16_t* __restrict__ KHp, const bf16_t* __restrict__ Vt, bf16_t* __restrict__ mixed, int gw, int NGW, int lane, LAS unsigned char* wl) {
;     ...
;             float cmid = carry;
;             if (!p1_dead) SB_HALF(p1, 3, 2, carry, cmid);
;             const bool done_mid = __all(cmid < 5.421010862427522e-20f);
;             if (!done_mid) SB_HALF(p0, 1, 0, cmid, carry); else carry = cmid;
.Lsb_p0_nomask:
	ds_read_b128 v[198:201], v159 offset:9216
	ds_read_b128 v[202:205], v159 offset:9248
	ds_read_b128 v[206:209], v159 offset:13856
	ds_read_b128 v[210:213], v159 offset:13824
	s_nop 6
	v_exp_f32_e32 v40, v40
	v_exp_f32_e32 v41, v41
	v_exp_f32_e32 v42, v42
	v_add_f32_e32 v40, 1.0, v40
	v_rcp_f32_e32 v40, v40
	v_add_f32_e32 v41, 1.0, v41
	v_rcp_f32_e32 v41, v41
	v_sub_f32_e32 v49, 1.0, v40
	v_exp_f32_e32 v43, v43
	v_mov_b32_e32 v51, v40
	v_mov_b32_e32 v40, v49
	v_add_f32_e32 v42, 1.0, v42
	v_rcp_f32_e32 v42, v42
	v_sub_f32_e32 v48, 1.0, v41
	v_exp_f32_e32 v44, v44
	v_add_f32_e32 v43, 1.0, v43
	v_mul_f32_e32 v50, v51, v41
	v_rcp_f32_e32 v43, v43
	v_sub_f32_e32 v49, 1.0, v42
	v_exp_f32_e32 v45, v45
	v_add_f32_e32 v44, 1.0, v44
	v_rcp_f32_e32 v44, v44
	v_mul_f32_e32 v51, v42, v50
	v_sub_f32_e32 v50, 1.0, v43
	v_exp_f32_e32 v46, v46
	v_add_f32_e32 v45, 1.0, v45
	v_rcp_f32_e32 v45, v45
	v_mul_f32_e32 v52, v43, v51
	v_sub_f32_e32 v51, 1.0, v44
	v_add_f32_e32 v46, 1.0, v46
	v_exp_f32_e32 v47, v47
	v_rcp_f32_e32 v46, v46
	v_mul_f32_e32 v53, v44, v52
	v_sub_f32_e32 v52, 1.0, v45
	v_exp_f32_e32 v32, v32
	v_add_f32_e32 v47, 1.0, v47
	v_mul_f32_e32 v54, v45, v53
	v_sub_f32_e32 v53, 1.0, v46
	v_rcp_f32_e32 v47, v47
	v_exp_f32_e32 v33, v33
	v_add_f32_e32 v32, 1.0, v32
	v_rcp_f32_e32 v32, v32
	v_exp_f32_e32 v34, v34
	v_add_f32_e32 v33, 1.0, v33
	v_mul_f32_e32 v55, v46, v54
	v_sub_f32_e32 v54, 1.0, v47
	v_rcp_f32_e32 v33, v33
	v_mul_f32_e32 v56, v47, v55
	v_sub_f32_e32 v55, 1.0, v32
	v_add_f32_e32 v34, 1.0, v34
	v_exp_f32_e32 v35, v35
	v_mov_b32_e32 v57, v32
	v_mov_b32_e32 v32, v55
	v_rcp_f32_e32 v34, v34
	v_sub_f32_e32 v55, 1.0, v33
	v_add_f32_e32 v35, 1.0, v35
	v_rcp_f32_e32 v35, v35
	v_sub_f32_e32 v58, 1.0, v34
	v_mul_f32_e32 v57, v57, v33
	s_nop 0
	v_mov_b32_e32 v59, v34
	v_mul_f32_e32 v34, v59, v57
	v_sub_f32_e32 v57, 1.0, v35
	v_mov_b32_e32 v60, v35
	v_exp_f32_e32 v35, v36
	s_nop 0
	v_add_f32_e32 v35, 1.0, v35
	v_rcp_f32_e32 v35, v35
	v_mul_f32_e32 v34, v60, v34
	v_sub_f32_e32 v36, 1.0, v35
	v_mov_b32_e32 v61, v35
	v_exp_f32_e32 v35, v37
	s_nop 0
	v_add_f32_e32 v35, 1.0, v35
	v_rcp_f32_e32 v35, v35
	v_mov_b32_e32 v62, v36
	v_mul_f32_e32 v34, v61, v34
	v_sub_f32_e32 v36, 1.0, v35
	v_mov_b32_e32 v163, v35
	v_exp_f32_e32 v35, v38
	s_nop 0
	v_add_f32_e32 v35, 1.0, v35
	v_rcp_f32_e32 v35, v35
	v_mov_b32_e32 v63, v36
	v_mul_f32_e32 v34, v163, v34
	v_sub_f32_e32 v36, 1.0, v35
	v_mov_b32_e32 v164, v35
	v_exp_f32_e32 v35, v39
	s_nop 0
	v_add_f32_e32 v35, 1.0, v35
	v_rcp_f32_e32 v35, v35
	v_mul_f32_e32 v34, v164, v34
	v_mov_b32_e32 v165, v36
	v_mov_b32_e32 v162, v35
	v_mul_f32_e32 v34, v162, v34
	v_sub_f32_e32 v36, 1.0, v35
	ds_bpermute_b32 v35, v156, v56
	ds_bpermute_b32 v167, v156, v34
	v_mov_b32_e32 v166, v36
	s_waitcnt lgkmcnt(1)
	v_mul_f32_e32 v36, v56, v35
	s_waitcnt lgkmcnt(0)
	v_mul_f32_e32 v168, v34, v167
	v_cndmask_b32_e64 v34, 1.0, v35, s[6:7]
	v_mul_f32_e32 v34, v161, v34
	v_mul_f32_e32 v37, v54, v34
	v_mul_f32_e32 v34, v47, v34
	v_mul_f32_e32 v38, v53, v34
	v_mul_f32_e32 v34, v46, v34
	v_mul_f32_e32 v56, v161, v36
	v_mul_f32_e32 v36, v52, v34
	v_mul_f32_e32 v34, v45, v34
	v_mul_f32_e32 v39, v51, v34
	v_mul_f32_e32 v34, v44, v34
	v_mul_f32_e32 v35, v50, v34
	v_mul_f32_e32 v34, v43, v34
	v_mul_f32_e32 v43, v49, v34
	v_mul_f32_e32 v34, v42, v34
	v_mul_f32_e32 v42, v48, v34
	v_mul_f32_e32 v34, v41, v34
	v_mul_f32_e32 v34, v40, v34
	v_cvt_pk_bf16_f32 v34, v34, v42
	v_cvt_pk_bf16_f32 v35, v43, v35
	v_cvt_pk_bf16_f32 v36, v39, v36
	v_cvt_pk_bf16_f32 v37, v38, v37
	s_waitcnt lgkmcnt(1)
	v_mfma_f32_32x32x16_bf16 v[16:31], v[202:205], v[34:37], v[16:31]
	v_mul_f32_e32 v161, v56, v168
	s_waitcnt lgkmcnt(0)
	v_mfma_f32_32x32x16_bf16 v[0:15], v[206:209], v[34:37], v[0:15]
	v_cndmask_b32_e64 v34, 1.0, v167, s[6:7]
	v_mul_f32_e32 v34, v56, v34
	v_mul_f32_e32 v35, v166, v34
	v_mul_f32_e32 v34, v162, v34
	v_mul_f32_e32 v36, v165, v34
	v_mul_f32_e32 v34, v164, v34
	v_mul_f32_e32 v37, v63, v34
	v_mul_f32_e32 v34, v163, v34
	v_mul_f32_e32 v42, v62, v34
	v_mul_f32_e32 v34, v61, v34
	v_mul_f32_e32 v43, v57, v34
	v_mul_f32_e32 v34, v60, v34
	v_mul_f32_e32 v44, v58, v34
	v_mul_f32_e32 v34, v59, v34
	v_mul_f32_e32 v33, v33, v34
	v_mul_f32_e32 v45, v55, v34
	v_mul_f32_e32 v32, v32, v33
	v_cvt_pk_bf16_f32 v32, v32, v45
	v_cvt_pk_bf16_f32 v33, v44, v43
	v_cvt_pk_bf16_f32 v34, v42, v37
	v_cvt_pk_bf16_f32 v35, v36, v35
	s_nop 1
	v_mfma_f32_32x32x16_bf16 v[16:31], v[198:201], v[32:35], v[16:31]
	s_waitcnt lgkmcnt(0)
	v_mfma_f32_32x32x16_bf16 v[0:15], v[210:213], v[32:35], v[0:15]
	s_branch .LBB0_416
